# index unit: key tiles staged once per workgroup into an LDS ring by LDS-DMA (swizzled), B fragments read from LDS by all 8 waves
# speedup vs baseline: 1.0097x; 1.0078x over previous
; #define LAS __attribute__((address_space(3)))
;     template <class T> __device__ __forceinline__ T* w(size_t off) const { return (T*)(pp->ws + off); }
; template <class T> __device__ __forceinline__ LAS T* opq(LAS T* p) { asm volatile("" : "+v"(p)); return p; }
; __device__ __forceinline__ unsigned ordkey(float f) { const unsigned u = __float_as_uint(f); return u ^ ((u >> 31) ? 0xFFFFFFFFu : 0x80000000u); }
; __device__ __forceinline__ void dsa_index_unit(const Ctx& c, int l, int b, int qb) {
;     ...
;     for (int pi = 0; pi < 2; ++pi) {
;         const int p = c.wave + 8 * pi;
;         const int tq = qb * 32 + 2 * p + hf;
;         bf16x8 Af[4];
;         { const bf16* qp = QI + (size_t)(r0 + 2 * p + ((n >> 2) & 1)) * 1024 + ((n & 3) + 4 * (n >> 3)) * 64 + 8 * hf;
; #pragma unroll
;           for (int ks = 0; ks < 4; ++ks) Af[ks] = *(const bf16x8*)(qp + 16 * ks); }
;         float wq[16];
;         { const float* wp = c.w<float>(WS_WI) + (size_t)(r0 + 2 * p + hf) * 16;
; #pragma unroll
;           for (int i = 0; i < 4; ++i) { const f32x4 w4 = *(const f32x4*)(wp + 4 * i); wq[4 * i] = w4[0] * 0.03125f; wq[4 * i + 1] = w4[1] * 0.03125f; wq[4 * i + 2] = w4[2] * 0.03125f; wq[4 * i + 3] = w4[3] * 0.03125f; } }
;         LAS unsigned* sk = opq((LAS unsigned*)c.lds + c.wave * 4096);
;         bf16x8 Bc[4];
;         { const bf16* kp = KI + (size_t)n * 64 + 8 * hf;
; #pragma unroll
;           for (int ks = 0; ks < 4; ++ks) Bc[ks] = *(const bf16x8*)(kp + 16 * ks); }
; #pragma unroll 1
;         for (int kt = 0; kt <= qb; ++kt) {
;             bf16x8 Bn[4];
;             { const int kn = kt < qb ? kt + 1 : kt; const bf16* kp = KI + (size_t)(kn * 32 + n) * 64 + 8 * hf;
; #pragma unroll
;               for (int ks = 0; ks < 4; ++ks) Bn[ks] = *(const bf16x8*)(kp + 16 * ks); }
;             f32x16 acc;
; #pragma unroll
;             for (int v = 0; v < 16; ++v) acc[v] = 0.f;
; #pragma unroll
;             for (int ks = 0; ks < 4; ++ks) acc = __builtin_amdgcn_mfma_f32_32x32x16_bf16(Af[ks], Bc[ks], acc, 0, 0, 0);
;             float sc = 0.f;
; #pragma unroll
;             for (int v = 0; v < 16; ++v) sc += wq[v] * fmaxf(acc[v], 0.f);
;             if (kt == qb && n > (tq & 31)) sc = -INFINITY;
;             sk[kt * 64 + lane] = ordkey(sc);
; #pragma unroll
;             for (int ks = 0; ks < 4; ++ks) Bc[ks] = Bn[ks];
;         }
.LBB0_1106:
	s_xor_b64 s[0:1], s[0:1], -1
	v_writelane_b32 v250, s0, 8
	v_readlane_b32 s4, v253, 35
	v_readlane_b32 s5, v253, 36
	v_writelane_b32 v250, s1, 9
	v_readlane_b32 s0, v251, 49
	s_add_i32 s0, s19, s0
	s_add_i32 s2, s0, s22
	v_or_b32_e32 v0, s2, v86
	v_ashrrev_i32_e32 v1, 31, v0
	v_lshlrev_b64 v[0:1], 11, v[0:1]
	v_lshl_add_u64 v[0:1], v[68:69], 0, v[0:1]
	global_load_dwordx4 v[18:21], v[0:1], off
	global_load_dwordx4 v[22:25], v[0:1], off offset:32
	global_load_dwordx4 v[26:29], v[0:1], off offset:64
	global_load_dwordx4 v[30:33], v[0:1], off offset:96
	v_add_u32_e32 v0, s2, v63
	v_ashrrev_i32_e32 v1, 31, v0
	v_lshlrev_b64 v[0:1], 6, v[0:1]
	v_lshl_add_u64 v[12:13], s[4:5], 0, v[0:1]
	global_load_dwordx4 v[0:3], v[12:13], off offset:48
	global_load_dwordx4 v[4:7], v[12:13], off offset:32
	global_load_dwordx4 v[8:11], v[12:13], off offset:16
	s_nop 0
	global_load_dwordx4 v[12:15], v[12:13], off
	v_readlane_b32 s1, v251, 50
	s_waitcnt vmcnt(3)
	v_pk_mul_f32 v[82:83], v[0:1], s[68:69] op_sel_hi:[1,0]
	s_waitcnt vmcnt(2)
	v_pk_mul_f32 v[78:79], v[4:5], s[68:69] op_sel_hi:[1,0]
	v_mov_b32_e32 v4, s1
	v_pk_mul_f32 v[84:85], v[2:3], s[68:69] op_sel_hi:[1,0]
	v_add_u32_e32 v5, s0, v63
	v_and_b32_e32 v5, 31, v5
	v_lshl_add_u32 v67, v66, 2, v4
	s_waitcnt vmcnt(0)
	v_mul_f32_e32 v88, 0x3d000000, v12
	v_mul_f32_e32 v89, 0x3d000000, v13
	v_mul_f32_e32 v90, 0x3d000000, v14
	v_mul_f32_e32 v91, 0x3d000000, v15
	v_mul_f32_e32 v92, 0x3d000000, v8
	v_mul_f32_e32 v93, 0x3d000000, v9
	v_pk_mul_f32 v[76:77], v[10:11], s[68:69] op_sel_hi:[1,0]
	v_pk_mul_f32 v[80:81], v[6:7], s[68:69] op_sel_hi:[1,0]
	v_cmp_gt_u32_e32 vcc, v65, v5
	v_mov_b32_e32 v94, v67
	s_mov_b32 s0, 0
	s_mov_b32 s44, 0
	v_readlane_b32 s53, v251, 50
	s_nop 3
	s_cmp_lt_u32 s53, 0x10000
	s_cselect_b32 s46, 1, 0
	s_lshr_b32 s52, s53, 4
	s_add_i32 s52, s52, 0x20000
	v_readfirstlane_b32 s48, v70
	v_readfirstlane_b32 s49, v71
	s_lshr_b32 s45, s53, 8
	s_and_b32 s45, s45, 0xc0
	v_add_u32_e32 v117, s45, v66
	v_lshrrev_b32_e32 v118, 3, v117
	v_and_b32_e32 v112, 7, v117
	v_and_b32_e32 v117, 7, v118
	v_xor_b32_e32 v112, v112, v117
	v_lshlrev_b32_e32 v112, 4, v112
	v_lshl_add_u32 v112, v118, 7, v112
	v_and_b32_e32 v117, 7, v65
	v_lshlrev_b32_e32 v118, 7, v65
	v_add_u32_e32 v118, 0x20000, v118
	v_add_u32_e32 v113, 0, v63
	v_xor_b32_e32 v113, v113, v117
	v_lshl_add_u32 v113, v113, 4, v118
	v_add_u32_e32 v114, 2, v63
	v_xor_b32_e32 v114, v114, v117
	v_lshl_add_u32 v114, v114, 4, v118
	v_add_u32_e32 v115, 4, v63
	v_xor_b32_e32 v115, v115, v117
	v_lshl_add_u32 v115, v115, 4, v118
	v_add_u32_e32 v116, 6, v63
	v_xor_b32_e32 v116, v116, v117
	v_lshl_add_u32 v116, v116, 4, v118
	s_cmp_lg_u32 s46, 0
	s_cbranch_scc0 .Lit0_pre_nodma
	s_mov_b32 s45, 0
	s_lshl_b32 s45, s45, 12
	s_add_u32 s50, s48, s45
	s_addc_u32 s51, s49, 0
	s_add_i32 m0, s52, 0
	s_nop 0
	global_load_lds_dwordx4 v112, s[50:51]
	s_mov_b32 s45, 1
	s_lshl_b32 s45, s45, 12
	s_add_u32 s50, s48, s45
	s_addc_u32 s51, s49, 0
	s_add_i32 m0, s52, 4096
	s_nop 0
	global_load_lds_dwordx4 v112, s[50:51]
	s_mov_b32 s45, 2
	s_lshl_b32 s45, s45, 12
	s_add_u32 s50, s48, s45
	s_addc_u32 s51, s49, 0
	s_add_i32 m0, s52, 8192
	s_nop 0
	global_load_lds_dwordx4 v112, s[50:51]
.Lit0_pre_nodma:
.LBB0_1107:
.Lit0_step0:
	s_waitcnt vmcnt(2)
	s_barrier
	ds_read_b128 v[46:49], v113 offset:0
	ds_read_b128 v[50:53], v114 offset:0
	ds_read_b128 v[54:57], v115 offset:0
	ds_read_b128 v[58:61], v116 offset:0
	s_cmp_lg_u32 s46, 0
	s_cbranch_scc0 .Lit0_nodma0
	s_add_i32 s45, s44, 3
	s_min_u32 s45, s45, s16
	s_lshl_b32 s45, s45, 12
	s_add_u32 s50, s48, s45
	s_addc_u32 s51, s49, 0
	s_add_i32 m0, s52, 12288
	s_nop 0
	global_load_lds_dwordx4 v112, s[50:51]
.Lit0_nodma0:
	s_cmp_eq_u32 s16, s44
	s_cselect_b64 s[0:1], -1, 0
	s_and_b64 s[0:1], s[0:1], vcc
	s_waitcnt lgkmcnt(0)
	v_mfma_f32_32x32x16_bf16 v[0:15], v[18:21], v[46:49], 0
	v_mfma_f32_32x32x16_bf16 v[0:15], v[22:25], v[50:53], v[0:15]
	v_mfma_f32_32x32x16_bf16 v[0:15], v[26:29], v[54:57], v[0:15]
	v_mfma_f32_32x32x16_bf16 v[0:15], v[30:33], v[58:61], v[0:15]
	s_nop 7
	s_nop 4
	v_max_f32_e32 v0, v0, v0
	v_max_f32_e32 v0, 0, v0
	v_fma_f32 v16, v88, v0, 0
	v_max_f32_e32 v0, v1, v1
	v_max_f32_e32 v0, 0, v0
	v_fmac_f32_e32 v16, v89, v0
	v_max_f32_e32 v0, v2, v2
	v_max_f32_e32 v0, 0, v0
	v_fmac_f32_e32 v16, v90, v0
	v_max_f32_e32 v0, v3, v3
	v_max_f32_e32 v0, 0, v0
	v_fmac_f32_e32 v16, v91, v0
	v_max_f32_e32 v0, v4, v4
	v_max_f32_e32 v0, 0, v0
	v_fmac_f32_e32 v16, v92, v0
	v_max_f32_e32 v0, v5, v5
	v_max_f32_e32 v0, 0, v0
	v_fmac_f32_e32 v16, v93, v0
	v_max_f32_e32 v0, v6, v6
	v_max_f32_e32 v1, v7, v7
	v_max_f32_e32 v0, 0, v0
	v_max_f32_e32 v1, 0, v1
	v_pk_mul_f32 v[0:1], v[76:77], v[0:1]
	s_nop 0
	v_add_f32_e32 v0, v0, v16
	v_add_f32_e32 v2, v1, v0
	v_max_f32_e32 v0, v8, v8
	v_max_f32_e32 v1, v9, v9
	v_max_f32_e32 v0, 0, v0
	v_max_f32_e32 v1, 0, v1
	v_pk_mul_f32 v[0:1], v[78:79], v[0:1]
	s_nop 0
	v_add_f32_e32 v0, v0, v2
	v_add_f32_e32 v2, v1, v0
	v_max_f32_e32 v0, v10, v10
	v_max_f32_e32 v1, v11, v11
	v_max_f32_e32 v0, 0, v0
	v_max_f32_e32 v1, 0, v1
	v_pk_mul_f32 v[0:1], v[80:81], v[0:1]
	s_nop 0
	v_add_f32_e32 v0, v0, v2
	v_add_f32_e32 v2, v1, v0
	v_max_f32_e32 v0, v12, v12
	v_max_f32_e32 v1, v13, v13
	v_max_f32_e32 v0, 0, v0
	v_max_f32_e32 v1, 0, v1
	v_pk_mul_f32 v[0:1], v[82:83], v[0:1]
	s_nop 0
	v_add_f32_e32 v0, v0, v2
	v_add_f32_e32 v2, v1, v0
	v_max_f32_e32 v0, v14, v14
	v_max_f32_e32 v1, v15, v15
	v_max_f32_e32 v0, 0, v0
	v_max_f32_e32 v1, 0, v1
	v_pk_mul_f32 v[0:1], v[84:85], v[0:1]
	s_nop 0
	v_add_f32_e32 v0, v0, v2
	v_add_f32_e32 v0, v1, v0
	v_cndmask_b32_e64 v0, v0, v139, s[0:1]
	v_cmp_lt_i32_e64 s[0:1], -1, v0
	s_nop 1
	v_cndmask_b32_e64 v1, -1, v140, s[0:1]
	v_xor_b32_e32 v0, v1, v0
	ds_write_b32 v94, v0
	v_add_u32_e32 v94, 0x100, v94
	s_add_i32 s44, s44, 1
	s_cmp_eq_u32 s18, s44
	s_cbranch_scc1 .Lit0_done
.Lit0_step1:
	s_waitcnt vmcnt(2)
	s_barrier
	ds_read_b128 v[46:49], v113 offset:4096
	ds_read_b128 v[50:53], v114 offset:4096
	ds_read_b128 v[54:57], v115 offset:4096
	ds_read_b128 v[58:61], v116 offset:4096
	s_cmp_lg_u32 s46, 0
	s_cbranch_scc0 .Lit0_nodma1
	s_add_i32 s45, s44, 3
	s_min_u32 s45, s45, s16
	s_lshl_b32 s45, s45, 12
	s_add_u32 s50, s48, s45
	s_addc_u32 s51, s49, 0
	s_add_i32 m0, s52, 0
	s_nop 0
	global_load_lds_dwordx4 v112, s[50:51]

; __device__ __forceinline__ void dsa_index_unit(const Ctx& c, int l, int b, int qb) {
;     ...
;         for (int kt = 0; kt <= qb; ++kt) {
;             bf16x8 Bn[4];
;             { const int kn = kt < qb ? kt + 1 : kt; const bf16* kp = KI + (size_t)(kn * 32 + n) * 64 + 8 * hf;
; #pragma unroll
;               for (int ks = 0; ks < 4; ++ks) Bn[ks] = *(const bf16x8*)(kp + 16 * ks); }
.Lit0_step2:
	s_waitcnt vmcnt(2)
	s_barrier
	ds_read_b128 v[46:49], v113 offset:8192
	ds_read_b128 v[50:53], v114 offset:8192
	ds_read_b128 v[54:57], v115 offset:8192
	ds_read_b128 v[58:61], v116 offset:8192
	s_cmp_lg_u32 s46, 0
	s_cbranch_scc0 .Lit0_nodma2
	s_add_i32 s45, s44, 3
	s_min_u32 s45, s45, s16
	s_lshl_b32 s45, s45, 12
	s_add_u32 s50, s48, s45
	s_addc_u32 s51, s49, 0
	s_add_i32 m0, s52, 4096
	s_nop 0
	global_load_lds_dwordx4 v112, s[50:51]

; __device__ __forceinline__ unsigned ordkey(float f) { const unsigned u = __float_as_uint(f); return u ^ ((u >> 31) ? 0xFFFFFFFFu : 0x80000000u); }
; __device__ __forceinline__ void dsa_index_unit(const Ctx& c, int l, int b, int qb) {
;     ...
;         for (int kt = 0; kt <= qb; ++kt) {
;             bf16x8 Bn[4];
;             { const int kn = kt < qb ? kt + 1 : kt; const bf16* kp = KI + (size_t)(kn * 32 + n) * 64 + 8 * hf;
; #pragma unroll
;               for (int ks = 0; ks < 4; ++ks) Bn[ks] = *(const bf16x8*)(kp + 16 * ks); }
;             f32x16 acc;
; #pragma unroll
;             for (int v = 0; v < 16; ++v) acc[v] = 0.f;
; #pragma unroll
;             for (int ks = 0; ks < 4; ++ks) acc = __builtin_amdgcn_mfma_f32_32x32x16_bf16(Af[ks], Bc[ks], acc, 0, 0, 0);
;             float sc = 0.f;
; #pragma unroll
;             for (int v = 0; v < 16; ++v) sc += wq[v] * fmaxf(acc[v], 0.f);
;             if (kt == qb && n > (tq & 31)) sc = -INFINITY;
;             sk[kt * 64 + lane] = ordkey(sc);
; #pragma unroll
;             for (int ks = 0; ks < 4; ++ks) Bc[ks] = Bn[ks];
;         }
;         unsigned key[64];
; #pragma unroll
;         for (int kt = 0; kt < 64; ++kt) { const unsigned kv = sk[kt * 64 + lane]; key[kt] = (kt <= qb) ? kv : 0u; }
.Lit0_step3:
	s_waitcnt vmcnt(2)
	s_barrier
	ds_read_b128 v[46:49], v113 offset:12288
	ds_read_b128 v[50:53], v114 offset:12288
	ds_read_b128 v[54:57], v115 offset:12288
	ds_read_b128 v[58:61], v116 offset:12288
	s_cmp_lg_u32 s46, 0
	s_cbranch_scc0 .Lit0_nodma3
	s_add_i32 s45, s44, 3
	s_min_u32 s45, s45, s16
	s_lshl_b32 s45, s45, 12
	s_add_u32 s50, s48, s45
	s_addc_u32 s51, s49, 0
	s_add_i32 m0, s52, 8192
	s_nop 0
	global_load_lds_dwordx4 v112, s[50:51]
.Lit0_nodma3:
	s_cmp_eq_u32 s16, s44
	s_cselect_b64 s[0:1], -1, 0
	s_and_b64 s[0:1], s[0:1], vcc
	s_waitcnt lgkmcnt(0)
	v_mfma_f32_32x32x16_bf16 v[0:15], v[18:21], v[46:49], 0
	v_mfma_f32_32x32x16_bf16 v[0:15], v[22:25], v[50:53], v[0:15]
	v_mfma_f32_32x32x16_bf16 v[0:15], v[26:29], v[54:57], v[0:15]
	v_mfma_f32_32x32x16_bf16 v[0:15], v[30:33], v[58:61], v[0:15]
	s_nop 7
	s_nop 4
	v_max_f32_e32 v0, v0, v0
	v_max_f32_e32 v0, 0, v0
	v_fma_f32 v16, v88, v0, 0
	v_max_f32_e32 v0, v1, v1
	v_max_f32_e32 v0, 0, v0
	v_fmac_f32_e32 v16, v89, v0
	v_max_f32_e32 v0, v2, v2
	v_max_f32_e32 v0, 0, v0
	v_fmac_f32_e32 v16, v90, v0
	v_max_f32_e32 v0, v3, v3
	v_max_f32_e32 v0, 0, v0
	v_fmac_f32_e32 v16, v91, v0
	v_max_f32_e32 v0, v4, v4
	v_max_f32_e32 v0, 0, v0
	v_fmac_f32_e32 v16, v92, v0
	v_max_f32_e32 v0, v5, v5
	v_max_f32_e32 v0, 0, v0
	v_fmac_f32_e32 v16, v93, v0
	v_max_f32_e32 v0, v6, v6
	v_max_f32_e32 v1, v7, v7
	v_max_f32_e32 v0, 0, v0
	v_max_f32_e32 v1, 0, v1
	v_pk_mul_f32 v[0:1], v[76:77], v[0:1]
	s_nop 0
	v_add_f32_e32 v0, v0, v16
	v_add_f32_e32 v2, v1, v0
	v_max_f32_e32 v0, v8, v8
	v_max_f32_e32 v1, v9, v9
	v_max_f32_e32 v0, 0, v0
	v_max_f32_e32 v1, 0, v1
	v_pk_mul_f32 v[0:1], v[78:79], v[0:1]
	s_nop 0
	v_add_f32_e32 v0, v0, v2
	v_add_f32_e32 v2, v1, v0
	v_max_f32_e32 v0, v10, v10
	v_max_f32_e32 v1, v11, v11
	v_max_f32_e32 v0, 0, v0
	v_max_f32_e32 v1, 0, v1
	v_pk_mul_f32 v[0:1], v[80:81], v[0:1]
	s_nop 0
	v_add_f32_e32 v0, v0, v2
	v_add_f32_e32 v2, v1, v0
	v_max_f32_e32 v0, v12, v12
	v_max_f32_e32 v1, v13, v13
	v_max_f32_e32 v0, 0, v0
	v_max_f32_e32 v1, 0, v1
	v_pk_mul_f32 v[0:1], v[82:83], v[0:1]
	s_nop 0
	v_add_f32_e32 v0, v0, v2
	v_add_f32_e32 v2, v1, v0
	v_max_f32_e32 v0, v14, v14
	v_max_f32_e32 v1, v15, v15
	v_max_f32_e32 v0, 0, v0
	v_max_f32_e32 v1, 0, v1
	v_pk_mul_f32 v[0:1], v[84:85], v[0:1]
	s_nop 0
	v_add_f32_e32 v0, v0, v2
	v_add_f32_e32 v0, v1, v0
	v_cndmask_b32_e64 v0, v0, v139, s[0:1]
	v_cmp_lt_i32_e64 s[0:1], -1, v0
	s_nop 1
	v_cndmask_b32_e64 v1, -1, v140, s[0:1]
	v_xor_b32_e32 v0, v1, v0
	ds_write_b32 v94, v0
	v_add_u32_e32 v94, 0x100, v94
	s_add_i32 s44, s44, 1
	s_cmp_eq_u32 s18, s44
	s_cbranch_scc1 .Lit0_done
	s_branch .Lit0_step0
.Lit0_done:
	s_waitcnt vmcnt(0)
	s_barrier
	ds_read2st64_b32 v[8:9], v67 offset1:1
	ds_read2st64_b32 v[6:7], v67 offset0:2 offset1:3
	ds_read2st64_b32 v[4:5], v67 offset0:4 offset1:5
	ds_read2st64_b32 v[2:3], v67 offset0:6 offset1:7
	ds_read2st64_b32 v[0:1], v67 offset0:8 offset1:9
	ds_read2st64_b32 v[10:11], v67 offset0:10 offset1:11
	ds_read2st64_b32 v[102:103], v67 offset0:62 offset1:63
	v_readlane_b32 s0, v250, 22
	v_readlane_b32 s1, v250, 23
	s_mov_b64 s[20:21], s[90:91]
	s_waitcnt lgkmcnt(2)
	v_cndmask_b32_e64 v101, v1, 0, s[0:1]
	v_readlane_b32 s0, v250, 16
	v_readlane_b32 s1, v250, 17
	s_waitcnt lgkmcnt(1)
	s_nop 0
	v_cndmask_b32_e64 v99, v10, 0, s[0:1]
	v_readlane_b32 s0, v250, 18
	v_readlane_b32 s1, v250, 19
	s_nop 1
	v_cndmask_b32_e64 v98, v11, 0, s[0:1]
	ds_read2st64_b32 v[10:11], v67 offset0:12 offset1:13
	v_readlane_b32 s0, v250, 26
	v_readlane_b32 s1, v250, 27
	s_waitcnt lgkmcnt(0)
	s_nop 0
	v_cndmask_b32_e64 v96, v10, 0, s[0:1]
	v_readlane_b32 s0, v250, 28
	v_readlane_b32 s1, v250, 29
	s_nop 1
	v_cndmask_b32_e64 v95, v11, 0, s[0:1]
	ds_read2st64_b32 v[10:11], v67 offset0:14 offset1:15
	v_readlane_b32 s0, v250, 30
	v_readlane_b32 s1, v250, 31
	s_waitcnt lgkmcnt(0)
	s_nop 0
	v_cndmask_b32_e64 v93, v10, 0, s[0:1]
	v_readlane_b32 s0, v250, 24
	v_readlane_b32 s1, v250, 25
	s_nop 1
	v_cndmask_b32_e64 v92, v11, 0, s[0:1]
	ds_read2st64_b32 v[10:11], v67 offset0:16 offset1:17
	v_readlane_b32 s0, v250, 40
	v_readlane_b32 s1, v250, 41
	s_waitcnt lgkmcnt(0)
	s_nop 0
	v_cndmask_b32_e64 v90, v10, 0, s[0:1]
	v_readlane_b32 s0, v250, 32
	v_readlane_b32 s1, v250, 33
	s_nop 1
	v_cndmask_b32_e64 v89, v11, 0, s[0:1]
	ds_read2st64_b32 v[10:11], v67 offset0:18 offset1:19
	v_readlane_b32 s0, v250, 10
	v_readlane_b32 s1, v250, 11
	s_waitcnt lgkmcnt(0)
	s_nop 0
	v_cndmask_b32_e64 v85, v10, 0, s[0:1]
	v_readlane_b32 s0, v250, 14
	v_readlane_b32 s1, v250, 15
	s_nop 1
	v_cndmask_b32_e64 v84, v11, 0, s[0:1]
	ds_read2st64_b32 v[10:11], v67 offset0:20 offset1:21
	v_readlane_b32 s0, v250, 34
	v_readlane_b32 s1, v250, 35
	s_waitcnt lgkmcnt(0)
	s_nop 0
	v_cndmask_b32_e64 v83, v10, 0, s[0:1]
	v_readlane_b32 s0, v250, 36
	v_readlane_b32 s1, v250, 37
	s_nop 1
	v_cndmask_b32_e64 v81, v11, 0, s[0:1]
	ds_read2st64_b32 v[10:11], v67 offset0:22 offset1:23
	v_readlane_b32 s0, v250, 38
	v_readlane_b32 s1, v250, 39
	s_waitcnt lgkmcnt(0)
	s_nop 0
	v_cndmask_b32_e64 v80, v10, 0, s[0:1]
	v_readlane_b32 s0, v252, 17
	v_readlane_b32 s1, v252, 18
	s_nop 1
	v_cndmask_b32_e64 v78, v11, 0, s[0:1]
	ds_read2st64_b32 v[10:11], v67 offset0:24 offset1:25
	v_readlane_b32 s0, v252, 19
	v_readlane_b32 s1, v252, 20
	s_waitcnt lgkmcnt(0)
	s_nop 0
	v_cndmask_b32_e64 v77, v10, 0, s[0:1]
	v_readlane_b32 s0, v252, 21
	v_readlane_b32 s1, v252, 22
	s_nop 1
	v_cndmask_b32_e64 v76, v11, 0, s[0:1]
	ds_read2st64_b32 v[10:11], v67 offset0:26 offset1:27
	v_readlane_b32 s0, v252, 23
	v_readlane_b32 s1, v252, 24
	s_waitcnt lgkmcnt(0)
; __device__ __forceinline__ void dsa_index_unit(const Ctx& c, int l, int b, int qb) {
;     ...
;         unsigned key[64];
; #pragma unroll
;         for (int kt = 0; kt < 64; ++kt) { const unsigned kv = sk[kt * 64 + lane]; key[kt] = (kt <= qb) ? kv : 0u; }
;         unsigned T = 0u;
	s_nop 0
	v_cndmask_b32_e64 v61, v10, 0, s[0:1]
	v_readlane_b32 s0, v252, 25
	v_readlane_b32 s1, v252, 26
	s_nop 1
	v_cndmask_b32_e64 v60, v11, 0, s[0:1]
	ds_read2st64_b32 v[10:11], v67 offset0:28 offset1:29
	v_readlane_b32 s0, v252, 27
	v_readlane_b32 s1, v252, 28
	s_waitcnt lgkmcnt(0)
	s_nop 0
	v_cndmask_b32_e64 v58, v10, 0, s[0:1]
	v_readlane_b32 s0, v252, 29
	v_readlane_b32 s1, v252, 30
	s_nop 1
	v_cndmask_b32_e64 v57, v11, 0, s[0:1]
	ds_read2st64_b32 v[10:11], v67 offset0:30 offset1:31
	v_readlane_b32 s0, v252, 31
	v_readlane_b32 s1, v252, 32
	s_waitcnt lgkmcnt(0)
	s_nop 0
	v_cndmask_b32_e64 v55, v10, 0, s[0:1]
	v_readlane_b32 s0, v252, 33
	v_readlane_b32 s1, v252, 34
	s_nop 1
	v_cndmask_b32_e64 v54, v11, 0, s[0:1]
	ds_read2st64_b32 v[10:11], v67 offset0:32 offset1:33
	v_readlane_b32 s0, v252, 35
	v_readlane_b32 s1, v252, 36
	s_waitcnt lgkmcnt(0)
	s_nop 0
	v_cndmask_b32_e64 v52, v10, 0, s[0:1]
	v_readlane_b32 s0, v252, 37
	v_readlane_b32 s1, v252, 38
	s_nop 1
	v_cndmask_b32_e64 v51, v11, 0, s[0:1]
	ds_read2st64_b32 v[10:11], v67 offset0:34 offset1:35
	v_readlane_b32 s0, v252, 39
	v_readlane_b32 s1, v252, 40
	s_waitcnt lgkmcnt(0)
	s_nop 0
	v_cndmask_b32_e64 v49, v10, 0, s[0:1]
	v_readlane_b32 s0, v252, 41
	v_readlane_b32 s1, v252, 42
	s_nop 1
	v_cndmask_b32_e64 v48, v11, 0, s[0:1]
	ds_read2st64_b32 v[10:11], v67 offset0:36 offset1:37
	v_readlane_b32 s0, v252, 43
	v_readlane_b32 s1, v252, 44
	s_waitcnt lgkmcnt(0)
	s_nop 0
	v_cndmask_b32_e64 v46, v10, 0, s[0:1]
	v_readlane_b32 s0, v252, 45
	v_readlane_b32 s1, v252, 46
	s_nop 1
	v_cndmask_b32_e64 v45, v11, 0, s[0:1]
	ds_read2st64_b32 v[10:11], v67 offset0:38 offset1:39
	v_readlane_b32 s0, v252, 47
	v_readlane_b32 s1, v252, 48
	s_waitcnt lgkmcnt(0)
	s_nop 0
	v_cndmask_b32_e64 v43, v10, 0, s[0:1]
	v_readlane_b32 s0, v252, 49
	v_readlane_b32 s1, v252, 50
	s_nop 1
	v_cndmask_b32_e64 v42, v11, 0, s[0:1]
	ds_read2st64_b32 v[10:11], v67 offset0:40 offset1:41
	v_readlane_b32 s0, v252, 51
	v_readlane_b32 s1, v252, 52
	s_waitcnt lgkmcnt(0)
	s_nop 0
	v_cndmask_b32_e64 v40, v10, 0, s[0:1]
	v_readlane_b32 s0, v252, 53
	v_readlane_b32 s1, v252, 54
	s_nop 1
	v_cndmask_b32_e64 v39, v11, 0, s[0:1]
	ds_read2st64_b32 v[10:11], v67 offset0:42 offset1:43
	v_readlane_b32 s0, v252, 55
	v_readlane_b32 s1, v252, 56
	s_waitcnt lgkmcnt(0)
	s_nop 0
	v_cndmask_b32_e64 v38, v10, 0, s[0:1]
	v_readlane_b32 s0, v252, 57
	v_readlane_b32 s1, v252, 58
	s_nop 1
	v_cndmask_b32_e64 v36, v11, 0, s[0:1]
	ds_read2st64_b32 v[10:11], v67 offset0:44 offset1:45
	v_readlane_b32 s0, v252, 59
	v_readlane_b32 s1, v252, 60
	s_waitcnt lgkmcnt(0)
	s_nop 0
	v_cndmask_b32_e64 v35, v10, 0, s[0:1]
	v_readlane_b32 s0, v252, 61
	v_readlane_b32 s1, v252, 62
	s_nop 1
	v_cndmask_b32_e64 v33, v11, 0, s[0:1]
	ds_read2st64_b32 v[10:11], v67 offset0:46 offset1:47
	v_readlane_b32 s0, v252, 63
	v_readlane_b32 s1, v253, 0
	s_waitcnt lgkmcnt(0)
	s_nop 0
	v_cndmask_b32_e64 v32, v10, 0, s[0:1]
	v_readlane_b32 s0, v253, 1
	v_readlane_b32 s1, v253, 2
	s_nop 1
	v_cndmask_b32_e64 v30, v11, 0, s[0:1]
	ds_read2st64_b32 v[10:11], v67 offset0:48 offset1:49
	v_readlane_b32 s0, v253, 3
	v_readlane_b32 s1, v253, 4
	s_waitcnt lgkmcnt(0)
	s_nop 0
	v_cndmask_b32_e64 v29, v10, 0, s[0:1]
	v_readlane_b32 s0, v253, 5
	v_readlane_b32 s1, v253, 6
	s_nop 1
	v_cndmask_b32_e64 v27, v11, 0, s[0:1]
	ds_read2st64_b32 v[10:11], v67 offset0:50 offset1:51
	v_readlane_b32 s0, v253, 7
	v_readlane_b32 s1, v253, 8
	s_waitcnt lgkmcnt(0)
	s_nop 0
	v_cndmask_b32_e64 v26, v10, 0, s[0:1]
	v_readlane_b32 s0, v253, 9
	v_readlane_b32 s1, v253, 10
	s_nop 1
	v_cndmask_b32_e64 v24, v11, 0, s[0:1]
	ds_read2st64_b32 v[10:11], v67 offset0:52 offset1:53
	v_readlane_b32 s0, v253, 11
	v_readlane_b32 s1, v253, 12
	s_waitcnt lgkmcnt(0)
	s_nop 0
	v_cndmask_b32_e64 v22, v10, 0, s[0:1]
	v_readlane_b32 s0, v253, 13
	v_readlane_b32 s1, v253, 14
	s_nop 1
	v_cndmask_b32_e64 v21, v11, 0, s[0:1]
	ds_read2st64_b32 v[10:11], v67 offset0:54 offset1:55
	v_readlane_b32 s0, v253, 15
	v_readlane_b32 s1, v253, 16
	s_waitcnt lgkmcnt(0)
	s_nop 0
	v_cndmask_b32_e64 v20, v10, 0, s[0:1]
	v_readlane_b32 s0, v253, 17
	v_readlane_b32 s1, v253, 18
	s_nop 1
	v_cndmask_b32_e64 v19, v11, 0, s[0:1]
	ds_read2st64_b32 v[10:11], v67 offset0:56 offset1:57
	v_readlane_b32 s0, v253, 19
	v_readlane_b32 s1, v253, 20
	s_waitcnt lgkmcnt(0)
	s_nop 0
	v_cndmask_b32_e64 v18, v10, 0, s[0:1]
	v_readlane_b32 s0, v253, 21
	v_readlane_b32 s1, v253, 22
	s_nop 1
	v_cndmask_b32_e64 v16, v11, 0, s[0:1]
	ds_read2st64_b32 v[10:11], v67 offset0:58 offset1:59
	v_readlane_b32 s0, v253, 23
	v_readlane_b32 s1, v253, 24
	s_waitcnt lgkmcnt(0)
	s_nop 0
	v_cndmask_b32_e64 v15, v10, 0, s[0:1]
	v_readlane_b32 s0, v253, 25
	v_readlane_b32 s1, v253, 26
	s_nop 1
	v_cndmask_b32_e64 v14, v11, 0, s[0:1]
	ds_read2st64_b32 v[10:11], v67 offset0:60 offset1:61
	v_readlane_b32 s0, v253, 27
	v_readlane_b32 s1, v253, 28
	s_waitcnt lgkmcnt(0)
	s_nop 0
	v_cndmask_b32_e64 v13, v10, 0, s[0:1]
	v_readlane_b32 s0, v253, 29
	v_readlane_b32 s1, v253, 30
	v_mov_b32_e32 v10, 0
	s_nop 0
	v_cndmask_b32_e64 v12, v11, 0, s[0:1]
	v_readlane_b32 s0, v253, 31
	v_readlane_b32 s1, v253, 32
	s_nop 1
	v_cndmask_b32_e64 v11, v102, 0, s[0:1]
	v_readlane_b32 s0, v253, 33
	v_readlane_b32 s1, v253, 34
	s_nop 1
	v_cndmask_b32_e64 v1, 0, v103, s[0:1]
	s_mov_b32 s0, 31
	s_mov_b64 s[46:47], 0

; #define LAS __attribute__((address_space(3)))
;     template <class T> __device__ __forceinline__ T* w(size_t off) const { return (T*)(pp->ws + off); }
; template <class T> __device__ __forceinline__ LAS T* opq(LAS T* p) { asm volatile("" : "+v"(p)); return p; }
; __device__ __forceinline__ unsigned ordkey(float f) { const unsigned u = __float_as_uint(f); return u ^ ((u >> 31) ? 0xFFFFFFFFu : 0x80000000u); }
; __device__ __forceinline__ void dsa_index_unit(const Ctx& c, int l, int b, int qb) {
;     ...
;     for (int pi = 0; pi < 2; ++pi) {
;         const int p = c.wave + 8 * pi;
;         const int tq = qb * 32 + 2 * p + hf;
;         bf16x8 Af[4];
;         { const bf16* qp = QI + (size_t)(r0 + 2 * p + ((n >> 2) & 1)) * 1024 + ((n & 3) + 4 * (n >> 3)) * 64 + 8 * hf;
; #pragma unroll
;           for (int ks = 0; ks < 4; ++ks) Af[ks] = *(const bf16x8*)(qp + 16 * ks); }
;         float wq[16];
;         { const float* wp = c.w<float>(WS_WI) + (size_t)(r0 + 2 * p + hf) * 16;
; #pragma unroll
;           for (int i = 0; i < 4; ++i) { const f32x4 w4 = *(const f32x4*)(wp + 4 * i); wq[4 * i] = w4[0] * 0.03125f; wq[4 * i + 1] = w4[1] * 0.03125f; wq[4 * i + 2] = w4[2] * 0.03125f; wq[4 * i + 3] = w4[3] * 0.03125f; } }
;         LAS unsigned* sk = opq((LAS unsigned*)c.lds + c.wave * 4096);
;         bf16x8 Bc[4];
;         { const bf16* kp = KI + (size_t)n * 64 + 8 * hf;
; #pragma unroll
;           for (int ks = 0; ks < 4; ++ks) Bc[ks] = *(const bf16x8*)(kp + 16 * ks); }
; #pragma unroll 1
;         for (int kt = 0; kt <= qb; ++kt) {
;             bf16x8 Bn[4];
;             { const int kn = kt < qb ? kt + 1 : kt; const bf16* kp = KI + (size_t)(kn * 32 + n) * 64 + 8 * hf;
; #pragma unroll
;               for (int ks = 0; ks < 4; ++ks) Bn[ks] = *(const bf16x8*)(kp + 16 * ks); }
;             f32x16 acc;
; #pragma unroll
;             for (int v = 0; v < 16; ++v) acc[v] = 0.f;
; #pragma unroll
;             for (int ks = 0; ks < 4; ++ks) acc = __builtin_amdgcn_mfma_f32_32x32x16_bf16(Af[ks], Bc[ks], acc, 0, 0, 0);
;             float sc = 0.f;
; #pragma unroll
;             for (int v = 0; v < 16; ++v) sc += wq[v] * fmaxf(acc[v], 0.f);
;             if (kt == qb && n > (tq & 31)) sc = -INFINITY;
;             sk[kt * 64 + lane] = ordkey(sc);
; #pragma unroll
;             for (int ks = 0; ks < 4; ++ks) Bc[ks] = Bn[ks];
;         }
.LBB0_2629:
	s_xor_b64 s[0:1], s[0:1], -1
	v_writelane_b32 v250, s0, 8
	v_readlane_b32 s2, v253, 35
	v_readlane_b32 s3, v253, 36
	v_writelane_b32 v250, s1, 9
	v_readlane_b32 s0, v251, 49
	s_add_i32 s0, s19, s0
	s_add_i32 s16, s0, s11
	v_or_b32_e32 v0, s16, v86
	v_ashrrev_i32_e32 v1, 31, v0
	v_lshlrev_b64 v[0:1], 11, v[0:1]
	v_lshl_add_u64 v[0:1], v[68:69], 0, v[0:1]
	global_load_dwordx4 v[18:21], v[0:1], off
	global_load_dwordx4 v[22:25], v[0:1], off offset:32
	global_load_dwordx4 v[26:29], v[0:1], off offset:64
	global_load_dwordx4 v[30:33], v[0:1], off offset:96
	v_add_u32_e32 v0, s16, v63
	v_ashrrev_i32_e32 v1, 31, v0
	v_lshlrev_b64 v[0:1], 6, v[0:1]
	v_lshl_add_u64 v[12:13], s[2:3], 0, v[0:1]
	global_load_dwordx4 v[0:3], v[12:13], off offset:48
	global_load_dwordx4 v[4:7], v[12:13], off offset:32
	global_load_dwordx4 v[8:11], v[12:13], off offset:16
	s_nop 0
	global_load_dwordx4 v[12:15], v[12:13], off
	v_readlane_b32 s1, v251, 50
	s_waitcnt vmcnt(3)
	v_pk_mul_f32 v[82:83], v[0:1], s[68:69] op_sel_hi:[1,0]
	s_waitcnt vmcnt(2)
	v_pk_mul_f32 v[78:79], v[4:5], s[68:69] op_sel_hi:[1,0]
	v_mov_b32_e32 v4, s1
	v_pk_mul_f32 v[84:85], v[2:3], s[68:69] op_sel_hi:[1,0]
	v_add_u32_e32 v5, s0, v63
	v_and_b32_e32 v5, 31, v5
	v_lshl_add_u32 v67, v66, 2, v4
	s_waitcnt vmcnt(0)
	v_mul_f32_e32 v88, 0x3d000000, v12
	v_mul_f32_e32 v89, 0x3d000000, v13
	v_mul_f32_e32 v90, 0x3d000000, v14
	v_mul_f32_e32 v91, 0x3d000000, v15
	v_mul_f32_e32 v92, 0x3d000000, v8
	v_mul_f32_e32 v93, 0x3d000000, v9
	v_pk_mul_f32 v[76:77], v[10:11], s[68:69] op_sel_hi:[1,0]
	v_pk_mul_f32 v[80:81], v[6:7], s[68:69] op_sel_hi:[1,0]
	v_cmp_gt_u32_e32 vcc, v65, v5
	v_mov_b32_e32 v94, v67
	s_mov_b32 s0, 0
	s_mov_b32 s44, 0
	v_readlane_b32 s53, v251, 50
	s_nop 3
	s_cmp_lt_u32 s53, 0x10000
	s_cselect_b32 s46, 1, 0
	s_lshr_b32 s52, s53, 4
	s_add_i32 s52, s52, 0x20000
	v_readfirstlane_b32 s48, v70
	v_readfirstlane_b32 s49, v71
	s_lshr_b32 s45, s53, 8
	s_and_b32 s45, s45, 0xc0
	v_add_u32_e32 v117, s45, v66
	v_lshrrev_b32_e32 v118, 3, v117
	v_and_b32_e32 v112, 7, v117
	v_and_b32_e32 v117, 7, v118
	v_xor_b32_e32 v112, v112, v117
	v_lshlrev_b32_e32 v112, 4, v112
	v_lshl_add_u32 v112, v118, 7, v112
	v_and_b32_e32 v117, 7, v65
	v_lshlrev_b32_e32 v118, 7, v65
	v_add_u32_e32 v118, 0x20000, v118
	v_add_u32_e32 v113, 0, v63
	v_xor_b32_e32 v113, v113, v117
	v_lshl_add_u32 v113, v113, 4, v118
	v_add_u32_e32 v114, 2, v63
	v_xor_b32_e32 v114, v114, v117
	v_lshl_add_u32 v114, v114, 4, v118
	v_add_u32_e32 v115, 4, v63
	v_xor_b32_e32 v115, v115, v117
	v_lshl_add_u32 v115, v115, 4, v118
	v_add_u32_e32 v116, 6, v63
	v_xor_b32_e32 v116, v116, v117
	v_lshl_add_u32 v116, v116, 4, v118
	s_cmp_lg_u32 s46, 0
	s_cbranch_scc0 .Lit1_pre_nodma
	s_mov_b32 s45, 0
	s_lshl_b32 s45, s45, 12
	s_add_u32 s50, s48, s45
	s_addc_u32 s51, s49, 0
	s_add_i32 m0, s52, 0
	s_nop 0
	global_load_lds_dwordx4 v112, s[50:51]
	s_mov_b32 s45, 1
	s_lshl_b32 s45, s45, 12
	s_add_u32 s50, s48, s45
	s_addc_u32 s51, s49, 0
	s_add_i32 m0, s52, 4096
	s_nop 0
	global_load_lds_dwordx4 v112, s[50:51]
	s_mov_b32 s45, 2
	s_lshl_b32 s45, s45, 12
	s_add_u32 s50, s48, s45
	s_addc_u32 s51, s49, 0
	s_add_i32 m0, s52, 8192
	s_nop 0
	global_load_lds_dwordx4 v112, s[50:51]
.Lit1_pre_nodma:
.LBB0_2630:
.Lit1_step0:
	s_waitcnt vmcnt(2)
	s_barrier
	ds_read_b128 v[46:49], v113 offset:0
	ds_read_b128 v[50:53], v114 offset:0
	ds_read_b128 v[54:57], v115 offset:0
	ds_read_b128 v[58:61], v116 offset:0
	s_cmp_lg_u32 s46, 0
	s_cbranch_scc0 .Lit1_nodma0
	s_add_i32 s45, s44, 3
	s_min_u32 s45, s45, s14
	s_lshl_b32 s45, s45, 12
	s_add_u32 s50, s48, s45
	s_addc_u32 s51, s49, 0
	s_add_i32 m0, s52, 12288
	s_nop 0
	global_load_lds_dwordx4 v112, s[50:51]
.Lit1_nodma0:
	s_cmp_eq_u32 s14, s44
	s_cselect_b64 s[0:1], -1, 0
	s_and_b64 s[0:1], s[0:1], vcc
	s_waitcnt lgkmcnt(0)
	v_mfma_f32_32x32x16_bf16 v[0:15], v[18:21], v[46:49], 0
	v_mfma_f32_32x32x16_bf16 v[0:15], v[22:25], v[50:53], v[0:15]
	v_mfma_f32_32x32x16_bf16 v[0:15], v[26:29], v[54:57], v[0:15]
	v_mfma_f32_32x32x16_bf16 v[0:15], v[30:33], v[58:61], v[0:15]
	s_nop 7
	s_nop 4
	v_max_f32_e32 v0, v0, v0
	v_max_f32_e32 v0, 0, v0
	v_fma_f32 v16, v88, v0, 0
	v_max_f32_e32 v0, v1, v1
	v_max_f32_e32 v0, 0, v0
	v_fmac_f32_e32 v16, v89, v0
	v_max_f32_e32 v0, v2, v2
	v_max_f32_e32 v0, 0, v0
	v_fmac_f32_e32 v16, v90, v0
	v_max_f32_e32 v0, v3, v3
	v_max_f32_e32 v0, 0, v0
	v_fmac_f32_e32 v16, v91, v0
	v_max_f32_e32 v0, v4, v4
	v_max_f32_e32 v0, 0, v0
	v_fmac_f32_e32 v16, v92, v0
	v_max_f32_e32 v0, v5, v5
	v_max_f32_e32 v0, 0, v0
	v_fmac_f32_e32 v16, v93, v0
	v_max_f32_e32 v0, v6, v6
	v_max_f32_e32 v1, v7, v7
	v_max_f32_e32 v0, 0, v0
	v_max_f32_e32 v1, 0, v1
	v_pk_mul_f32 v[0:1], v[76:77], v[0:1]
	s_nop 0
	v_add_f32_e32 v0, v0, v16
	v_add_f32_e32 v2, v1, v0
	v_max_f32_e32 v0, v8, v8
	v_max_f32_e32 v1, v9, v9
	v_max_f32_e32 v0, 0, v0
	v_max_f32_e32 v1, 0, v1
	v_pk_mul_f32 v[0:1], v[78:79], v[0:1]
	s_nop 0
	v_add_f32_e32 v0, v0, v2
	v_add_f32_e32 v2, v1, v0
	v_max_f32_e32 v0, v10, v10
	v_max_f32_e32 v1, v11, v11
	v_max_f32_e32 v0, 0, v0
	v_max_f32_e32 v1, 0, v1
	v_pk_mul_f32 v[0:1], v[80:81], v[0:1]
	s_nop 0
	v_add_f32_e32 v0, v0, v2
	v_add_f32_e32 v2, v1, v0
	v_max_f32_e32 v0, v12, v12
	v_max_f32_e32 v1, v13, v13
	v_max_f32_e32 v0, 0, v0
	v_max_f32_e32 v1, 0, v1
	v_pk_mul_f32 v[0:1], v[82:83], v[0:1]
	s_nop 0
	v_add_f32_e32 v0, v0, v2
	v_add_f32_e32 v2, v1, v0
	v_max_f32_e32 v0, v14, v14
	v_max_f32_e32 v1, v15, v15
	v_max_f32_e32 v0, 0, v0
	v_max_f32_e32 v1, 0, v1
	v_pk_mul_f32 v[0:1], v[84:85], v[0:1]
	s_nop 0
	v_add_f32_e32 v0, v0, v2
	v_add_f32_e32 v0, v1, v0
	v_cndmask_b32_e64 v0, v0, v139, s[0:1]
	v_cmp_lt_i32_e64 s[0:1], -1, v0
	s_nop 1
	v_cndmask_b32_e64 v1, -1, v140, s[0:1]
	v_xor_b32_e32 v0, v1, v0
	ds_write_b32 v94, v0
	v_add_u32_e32 v94, 0x100, v94
	s_add_i32 s44, s44, 1
	s_cmp_eq_u32 s18, s44
	s_cbranch_scc1 .Lit1_done
.Lit1_step1:
	s_waitcnt vmcnt(2)
	s_barrier
	ds_read_b128 v[46:49], v113 offset:4096
	ds_read_b128 v[50:53], v114 offset:4096
	ds_read_b128 v[54:57], v115 offset:4096
	ds_read_b128 v[58:61], v116 offset:4096
	s_cmp_lg_u32 s46, 0
	s_cbranch_scc0 .Lit1_nodma1
	s_add_i32 s45, s44, 3
	s_min_u32 s45, s45, s14
	s_lshl_b32 s45, s45, 12
	s_add_u32 s50, s48, s45
	s_addc_u32 s51, s49, 0
	s_add_i32 m0, s52, 0
	s_nop 0
	global_load_lds_dwordx4 v112, s[50:51]

; __device__ __forceinline__ void dsa_index_unit(const Ctx& c, int l, int b, int qb) {
;     ...
;         for (int kt = 0; kt <= qb; ++kt) {
;             bf16x8 Bn[4];
;             { const int kn = kt < qb ? kt + 1 : kt; const bf16* kp = KI + (size_t)(kn * 32 + n) * 64 + 8 * hf;
; #pragma unroll
;               for (int ks = 0; ks < 4; ++ks) Bn[ks] = *(const bf16x8*)(kp + 16 * ks); }
.Lit1_step2:
	s_waitcnt vmcnt(2)
	s_barrier
	ds_read_b128 v[46:49], v113 offset:8192
	ds_read_b128 v[50:53], v114 offset:8192
	ds_read_b128 v[54:57], v115 offset:8192
	ds_read_b128 v[58:61], v116 offset:8192
	s_cmp_lg_u32 s46, 0
	s_cbranch_scc0 .Lit1_nodma2
	s_add_i32 s45, s44, 3
	s_min_u32 s45, s45, s14
	s_lshl_b32 s45, s45, 12
	s_add_u32 s50, s48, s45
	s_addc_u32 s51, s49, 0
	s_add_i32 m0, s52, 4096
	s_nop 0
	global_load_lds_dwordx4 v112, s[50:51]

; __device__ __forceinline__ unsigned ordkey(float f) { const unsigned u = __float_as_uint(f); return u ^ ((u >> 31) ? 0xFFFFFFFFu : 0x80000000u); }
; __device__ __forceinline__ void dsa_index_unit(const Ctx& c, int l, int b, int qb) {
;     ...
;         for (int kt = 0; kt <= qb; ++kt) {
;             bf16x8 Bn[4];
;             { const int kn = kt < qb ? kt + 1 : kt; const bf16* kp = KI + (size_t)(kn * 32 + n) * 64 + 8 * hf;
; #pragma unroll
;               for (int ks = 0; ks < 4; ++ks) Bn[ks] = *(const bf16x8*)(kp + 16 * ks); }
;             f32x16 acc;
; #pragma unroll
;             for (int v = 0; v < 16; ++v) acc[v] = 0.f;
; #pragma unroll
;             for (int ks = 0; ks < 4; ++ks) acc = __builtin_amdgcn_mfma_f32_32x32x16_bf16(Af[ks], Bc[ks], acc, 0, 0, 0);
;             float sc = 0.f;
; #pragma unroll
;             for (int v = 0; v < 16; ++v) sc += wq[v] * fmaxf(acc[v], 0.f);
;             if (kt == qb && n > (tq & 31)) sc = -INFINITY;
;             sk[kt * 64 + lane] = ordkey(sc);
; #pragma unroll
;             for (int ks = 0; ks < 4; ++ks) Bc[ks] = Bn[ks];
;         }
;         unsigned key[64];
; #pragma unroll
;         for (int kt = 0; kt < 64; ++kt) { const unsigned kv = sk[kt * 64 + lane]; key[kt] = (kt <= qb) ? kv : 0u; }
.Lit1_step3:
	s_waitcnt vmcnt(2)
	s_barrier
	ds_read_b128 v[46:49], v113 offset:12288
	ds_read_b128 v[50:53], v114 offset:12288
	ds_read_b128 v[54:57], v115 offset:12288
	ds_read_b128 v[58:61], v116 offset:12288
	s_cmp_lg_u32 s46, 0
	s_cbranch_scc0 .Lit1_nodma3
	s_add_i32 s45, s44, 3
	s_min_u32 s45, s45, s14
	s_lshl_b32 s45, s45, 12
	s_add_u32 s50, s48, s45
	s_addc_u32 s51, s49, 0
	s_add_i32 m0, s52, 8192
	s_nop 0
	global_load_lds_dwordx4 v112, s[50:51]
.Lit1_nodma3:
	s_cmp_eq_u32 s14, s44
	s_cselect_b64 s[0:1], -1, 0
	s_and_b64 s[0:1], s[0:1], vcc
	s_waitcnt lgkmcnt(0)
	v_mfma_f32_32x32x16_bf16 v[0:15], v[18:21], v[46:49], 0
	v_mfma_f32_32x32x16_bf16 v[0:15], v[22:25], v[50:53], v[0:15]
	v_mfma_f32_32x32x16_bf16 v[0:15], v[26:29], v[54:57], v[0:15]
	v_mfma_f32_32x32x16_bf16 v[0:15], v[30:33], v[58:61], v[0:15]
	s_nop 7
	s_nop 4
	v_max_f32_e32 v0, v0, v0
	v_max_f32_e32 v0, 0, v0
	v_fma_f32 v16, v88, v0, 0
	v_max_f32_e32 v0, v1, v1
	v_max_f32_e32 v0, 0, v0
	v_fmac_f32_e32 v16, v89, v0
	v_max_f32_e32 v0, v2, v2
	v_max_f32_e32 v0, 0, v0
	v_fmac_f32_e32 v16, v90, v0
	v_max_f32_e32 v0, v3, v3
	v_max_f32_e32 v0, 0, v0
	v_fmac_f32_e32 v16, v91, v0
	v_max_f32_e32 v0, v4, v4
	v_max_f32_e32 v0, 0, v0
	v_fmac_f32_e32 v16, v92, v0
	v_max_f32_e32 v0, v5, v5
	v_max_f32_e32 v0, 0, v0
	v_fmac_f32_e32 v16, v93, v0
	v_max_f32_e32 v0, v6, v6
	v_max_f32_e32 v1, v7, v7
	v_max_f32_e32 v0, 0, v0
	v_max_f32_e32 v1, 0, v1
	v_pk_mul_f32 v[0:1], v[76:77], v[0:1]
	s_nop 0
	v_add_f32_e32 v0, v0, v16
	v_add_f32_e32 v2, v1, v0
	v_max_f32_e32 v0, v8, v8
	v_max_f32_e32 v1, v9, v9
	v_max_f32_e32 v0, 0, v0
	v_max_f32_e32 v1, 0, v1
	v_pk_mul_f32 v[0:1], v[78:79], v[0:1]
	s_nop 0
	v_add_f32_e32 v0, v0, v2
	v_add_f32_e32 v2, v1, v0
	v_max_f32_e32 v0, v10, v10
	v_max_f32_e32 v1, v11, v11
	v_max_f32_e32 v0, 0, v0
	v_max_f32_e32 v1, 0, v1
	v_pk_mul_f32 v[0:1], v[80:81], v[0:1]
	s_nop 0
	v_add_f32_e32 v0, v0, v2
	v_add_f32_e32 v2, v1, v0
	v_max_f32_e32 v0, v12, v12
	v_max_f32_e32 v1, v13, v13
	v_max_f32_e32 v0, 0, v0
	v_max_f32_e32 v1, 0, v1
	v_pk_mul_f32 v[0:1], v[82:83], v[0:1]
	s_nop 0
	v_add_f32_e32 v0, v0, v2
	v_add_f32_e32 v2, v1, v0
	v_max_f32_e32 v0, v14, v14
	v_max_f32_e32 v1, v15, v15
	v_max_f32_e32 v0, 0, v0
	v_max_f32_e32 v1, 0, v1
	v_pk_mul_f32 v[0:1], v[84:85], v[0:1]
	s_nop 0
	v_add_f32_e32 v0, v0, v2
	v_add_f32_e32 v0, v1, v0
	v_cndmask_b32_e64 v0, v0, v139, s[0:1]
	v_cmp_lt_i32_e64 s[0:1], -1, v0
	s_nop 1
	v_cndmask_b32_e64 v1, -1, v140, s[0:1]
	v_xor_b32_e32 v0, v1, v0
	ds_write_b32 v94, v0
	v_add_u32_e32 v94, 0x100, v94
	s_add_i32 s44, s44, 1
	s_cmp_eq_u32 s18, s44
	s_cbranch_scc1 .Lit1_done
	s_branch .Lit1_step0
.Lit1_done:
	s_waitcnt vmcnt(0)
	s_barrier
	ds_read2st64_b32 v[8:9], v67 offset1:1
	ds_read2st64_b32 v[6:7], v67 offset0:2 offset1:3
	ds_read2st64_b32 v[4:5], v67 offset0:4 offset1:5
	ds_read2st64_b32 v[2:3], v67 offset0:6 offset1:7
	ds_read2st64_b32 v[0:1], v67 offset0:8 offset1:9
	ds_read2st64_b32 v[10:11], v67 offset0:10 offset1:11
	ds_read2st64_b32 v[102:103], v67 offset0:62 offset1:63
	v_readlane_b32 s0, v250, 22
	v_readlane_b32 s1, v250, 23
	s_mov_b32 s22, s11
	s_mov_b64 s[20:21], s[90:91]
	s_waitcnt lgkmcnt(2)
	v_cndmask_b32_e64 v101, v1, 0, s[0:1]
	v_readlane_b32 s0, v250, 16
	v_readlane_b32 s1, v250, 17
	s_waitcnt lgkmcnt(1)
	s_nop 0
	v_cndmask_b32_e64 v99, v10, 0, s[0:1]
	v_readlane_b32 s0, v250, 18
	v_readlane_b32 s1, v250, 19
	s_nop 1
	v_cndmask_b32_e64 v98, v11, 0, s[0:1]
	ds_read2st64_b32 v[10:11], v67 offset0:12 offset1:13
	v_readlane_b32 s0, v250, 26
	v_readlane_b32 s1, v250, 27
	s_waitcnt lgkmcnt(0)
	s_nop 0
	v_cndmask_b32_e64 v96, v10, 0, s[0:1]
	v_readlane_b32 s0, v250, 28
	v_readlane_b32 s1, v250, 29
	s_nop 1
	v_cndmask_b32_e64 v95, v11, 0, s[0:1]
	ds_read2st64_b32 v[10:11], v67 offset0:14 offset1:15
	v_readlane_b32 s0, v250, 30
	v_readlane_b32 s1, v250, 31
	s_waitcnt lgkmcnt(0)
	s_nop 0
	v_cndmask_b32_e64 v93, v10, 0, s[0:1]
	v_readlane_b32 s0, v250, 24
	v_readlane_b32 s1, v250, 25
	s_nop 1
	v_cndmask_b32_e64 v92, v11, 0, s[0:1]
	ds_read2st64_b32 v[10:11], v67 offset0:16 offset1:17
	v_readlane_b32 s0, v250, 40
	v_readlane_b32 s1, v250, 41
	s_waitcnt lgkmcnt(0)
	s_nop 0
	v_cndmask_b32_e64 v90, v10, 0, s[0:1]
	v_readlane_b32 s0, v250, 32
	v_readlane_b32 s1, v250, 33
	s_nop 1
	v_cndmask_b32_e64 v89, v11, 0, s[0:1]
	ds_read2st64_b32 v[10:11], v67 offset0:18 offset1:19
	v_readlane_b32 s0, v250, 10
	v_readlane_b32 s1, v250, 11
	s_waitcnt lgkmcnt(0)
	s_nop 0
	v_cndmask_b32_e64 v85, v10, 0, s[0:1]
	v_readlane_b32 s0, v250, 14
	v_readlane_b32 s1, v250, 15
	s_nop 1
	v_cndmask_b32_e64 v84, v11, 0, s[0:1]
	ds_read2st64_b32 v[10:11], v67 offset0:20 offset1:21
	v_readlane_b32 s0, v250, 34
	v_readlane_b32 s1, v250, 35
	s_waitcnt lgkmcnt(0)
	s_nop 0
	v_cndmask_b32_e64 v83, v10, 0, s[0:1]
	v_readlane_b32 s0, v250, 36
	v_readlane_b32 s1, v250, 37
	s_nop 1
	v_cndmask_b32_e64 v81, v11, 0, s[0:1]
	ds_read2st64_b32 v[10:11], v67 offset0:22 offset1:23
	v_readlane_b32 s0, v250, 38
	v_readlane_b32 s1, v250, 39
	s_waitcnt lgkmcnt(0)
	s_nop 0
	v_cndmask_b32_e64 v80, v10, 0, s[0:1]
	v_readlane_b32 s0, v252, 17
	v_readlane_b32 s1, v252, 18
	s_nop 1
	v_cndmask_b32_e64 v78, v11, 0, s[0:1]
	ds_read2st64_b32 v[10:11], v67 offset0:24 offset1:25
	v_readlane_b32 s0, v252, 19
	v_readlane_b32 s1, v252, 20
	s_waitcnt lgkmcnt(0)
	s_nop 0
	v_cndmask_b32_e64 v77, v10, 0, s[0:1]
	v_readlane_b32 s0, v252, 21
	v_readlane_b32 s1, v252, 22
	s_nop 1
	v_cndmask_b32_e64 v76, v11, 0, s[0:1]
	ds_read2st64_b32 v[10:11], v67 offset0:26 offset1:27
	v_readlane_b32 s0, v252, 23
	v_readlane_b32 s1, v252, 24
	s_waitcnt lgkmcnt(0)
; __device__ __forceinline__ void dsa_index_unit(const Ctx& c, int l, int b, int qb) {
;     ...
;         unsigned key[64];
; #pragma unroll
;         for (int kt = 0; kt < 64; ++kt) { const unsigned kv = sk[kt * 64 + lane]; key[kt] = (kt <= qb) ? kv : 0u; }
;         unsigned T = 0u;
	s_nop 0
	v_cndmask_b32_e64 v61, v10, 0, s[0:1]
	v_readlane_b32 s0, v252, 25
	v_readlane_b32 s1, v252, 26
	s_nop 1
	v_cndmask_b32_e64 v60, v11, 0, s[0:1]
	ds_read2st64_b32 v[10:11], v67 offset0:28 offset1:29
	v_readlane_b32 s0, v252, 27
	v_readlane_b32 s1, v252, 28
	s_waitcnt lgkmcnt(0)
	s_nop 0
	v_cndmask_b32_e64 v58, v10, 0, s[0:1]
	v_readlane_b32 s0, v252, 29
	v_readlane_b32 s1, v252, 30
	s_nop 1
	v_cndmask_b32_e64 v57, v11, 0, s[0:1]
	ds_read2st64_b32 v[10:11], v67 offset0:30 offset1:31
	v_readlane_b32 s0, v252, 31
	v_readlane_b32 s1, v252, 32
	s_waitcnt lgkmcnt(0)
	s_nop 0
	v_cndmask_b32_e64 v55, v10, 0, s[0:1]
	v_readlane_b32 s0, v252, 33
	v_readlane_b32 s1, v252, 34
	s_nop 1
	v_cndmask_b32_e64 v54, v11, 0, s[0:1]
	ds_read2st64_b32 v[10:11], v67 offset0:32 offset1:33
	v_readlane_b32 s0, v252, 35
	v_readlane_b32 s1, v252, 36
	s_waitcnt lgkmcnt(0)
	s_nop 0
	v_cndmask_b32_e64 v52, v10, 0, s[0:1]
	v_readlane_b32 s0, v252, 37
	v_readlane_b32 s1, v252, 38
	s_nop 1
	v_cndmask_b32_e64 v51, v11, 0, s[0:1]
	ds_read2st64_b32 v[10:11], v67 offset0:34 offset1:35
	v_readlane_b32 s0, v252, 39
	v_readlane_b32 s1, v252, 40
	s_waitcnt lgkmcnt(0)
	s_nop 0
	v_cndmask_b32_e64 v49, v10, 0, s[0:1]
	v_readlane_b32 s0, v252, 41
	v_readlane_b32 s1, v252, 42
	s_nop 1
	v_cndmask_b32_e64 v48, v11, 0, s[0:1]
	ds_read2st64_b32 v[10:11], v67 offset0:36 offset1:37
	v_readlane_b32 s0, v252, 43
	v_readlane_b32 s1, v252, 44
	s_waitcnt lgkmcnt(0)
	s_nop 0
	v_cndmask_b32_e64 v46, v10, 0, s[0:1]
	v_readlane_b32 s0, v252, 45
	v_readlane_b32 s1, v252, 46
	s_nop 1
	v_cndmask_b32_e64 v45, v11, 0, s[0:1]
	ds_read2st64_b32 v[10:11], v67 offset0:38 offset1:39
	v_readlane_b32 s0, v252, 47
	v_readlane_b32 s1, v252, 48
	s_waitcnt lgkmcnt(0)
	s_nop 0
	v_cndmask_b32_e64 v43, v10, 0, s[0:1]
	v_readlane_b32 s0, v252, 49
	v_readlane_b32 s1, v252, 50
	s_nop 1
	v_cndmask_b32_e64 v42, v11, 0, s[0:1]
	ds_read2st64_b32 v[10:11], v67 offset0:40 offset1:41
	v_readlane_b32 s0, v252, 51
	v_readlane_b32 s1, v252, 52
	s_waitcnt lgkmcnt(0)
	s_nop 0
	v_cndmask_b32_e64 v40, v10, 0, s[0:1]
	v_readlane_b32 s0, v252, 53
	v_readlane_b32 s1, v252, 54
	s_nop 1
	v_cndmask_b32_e64 v39, v11, 0, s[0:1]
	ds_read2st64_b32 v[10:11], v67 offset0:42 offset1:43
	v_readlane_b32 s0, v252, 55
	v_readlane_b32 s1, v252, 56
	s_waitcnt lgkmcnt(0)
	s_nop 0
	v_cndmask_b32_e64 v38, v10, 0, s[0:1]
	v_readlane_b32 s0, v252, 57
	v_readlane_b32 s1, v252, 58
	s_nop 1
	v_cndmask_b32_e64 v36, v11, 0, s[0:1]
	ds_read2st64_b32 v[10:11], v67 offset0:44 offset1:45
	v_readlane_b32 s0, v252, 59
	v_readlane_b32 s1, v252, 60
	s_waitcnt lgkmcnt(0)
	s_nop 0
	v_cndmask_b32_e64 v35, v10, 0, s[0:1]
	v_readlane_b32 s0, v252, 61
	v_readlane_b32 s1, v252, 62
	s_nop 1
	v_cndmask_b32_e64 v33, v11, 0, s[0:1]
	ds_read2st64_b32 v[10:11], v67 offset0:46 offset1:47
	v_readlane_b32 s0, v252, 63
	v_readlane_b32 s1, v253, 0
	s_waitcnt lgkmcnt(0)
	s_nop 0
	v_cndmask_b32_e64 v32, v10, 0, s[0:1]
	v_readlane_b32 s0, v253, 1
	v_readlane_b32 s1, v253, 2
	s_nop 1
	v_cndmask_b32_e64 v30, v11, 0, s[0:1]
	ds_read2st64_b32 v[10:11], v67 offset0:48 offset1:49
	v_readlane_b32 s0, v253, 3
	v_readlane_b32 s1, v253, 4
	s_waitcnt lgkmcnt(0)
	s_nop 0
	v_cndmask_b32_e64 v29, v10, 0, s[0:1]
	v_readlane_b32 s0, v253, 5
	v_readlane_b32 s1, v253, 6
	s_nop 1
	v_cndmask_b32_e64 v27, v11, 0, s[0:1]
	ds_read2st64_b32 v[10:11], v67 offset0:50 offset1:51
	v_readlane_b32 s0, v253, 7
	v_readlane_b32 s1, v253, 8
	s_waitcnt lgkmcnt(0)
	s_nop 0
	v_cndmask_b32_e64 v26, v10, 0, s[0:1]
	v_readlane_b32 s0, v253, 9
	v_readlane_b32 s1, v253, 10
	s_nop 1
	v_cndmask_b32_e64 v24, v11, 0, s[0:1]
	ds_read2st64_b32 v[10:11], v67 offset0:52 offset1:53
	v_readlane_b32 s0, v253, 11
	v_readlane_b32 s1, v253, 12
	s_waitcnt lgkmcnt(0)
	s_nop 0
	v_cndmask_b32_e64 v22, v10, 0, s[0:1]
	v_readlane_b32 s0, v253, 13
	v_readlane_b32 s1, v253, 14
	s_nop 1
	v_cndmask_b32_e64 v21, v11, 0, s[0:1]
	ds_read2st64_b32 v[10:11], v67 offset0:54 offset1:55
	v_readlane_b32 s0, v253, 15
	v_readlane_b32 s1, v253, 16
	s_waitcnt lgkmcnt(0)
	s_nop 0
	v_cndmask_b32_e64 v20, v10, 0, s[0:1]
	v_readlane_b32 s0, v253, 17
	v_readlane_b32 s1, v253, 18
	s_nop 1
	v_cndmask_b32_e64 v19, v11, 0, s[0:1]
	ds_read2st64_b32 v[10:11], v67 offset0:56 offset1:57
	v_readlane_b32 s0, v253, 19
	v_readlane_b32 s1, v253, 20
	s_waitcnt lgkmcnt(0)
	s_nop 0
	v_cndmask_b32_e64 v18, v10, 0, s[0:1]
	v_readlane_b32 s0, v253, 21
	v_readlane_b32 s1, v253, 22
	s_nop 1
	v_cndmask_b32_e64 v16, v11, 0, s[0:1]
	ds_read2st64_b32 v[10:11], v67 offset0:58 offset1:59
	v_readlane_b32 s0, v253, 23
	v_readlane_b32 s1, v253, 24
	s_waitcnt lgkmcnt(0)
	s_nop 0
	v_cndmask_b32_e64 v15, v10, 0, s[0:1]
	v_readlane_b32 s0, v253, 25
	v_readlane_b32 s1, v253, 26
	s_nop 1
	v_cndmask_b32_e64 v14, v11, 0, s[0:1]
	ds_read2st64_b32 v[10:11], v67 offset0:60 offset1:61
	v_readlane_b32 s0, v253, 27
	v_readlane_b32 s1, v253, 28
	s_waitcnt lgkmcnt(0)
	s_nop 0
	v_cndmask_b32_e64 v13, v10, 0, s[0:1]
	v_readlane_b32 s0, v253, 29
	v_readlane_b32 s1, v253, 30
	v_mov_b32_e32 v10, 0
	s_nop 0
	v_cndmask_b32_e64 v12, v11, 0, s[0:1]
	v_readlane_b32 s0, v253, 31
	v_readlane_b32 s1, v253, 32
	s_nop 1
	v_cndmask_b32_e64 v11, v102, 0, s[0:1]
	v_readlane_b32 s0, v253, 33
	v_readlane_b32 s1, v253, 34
	s_nop 1
	v_cndmask_b32_e64 v1, 0, v103, s[0:1]
	s_mov_b32 s0, 31
	s_mov_b64 s[46:47], 0
